# peeled first K iteration also in QKV and conv-in GEMM loops
# speedup vs baseline: 1.0243x; 1.0010x over previous
; #define PG8_STAGE(bufoff, gbase, voff) do { _Pragma("unroll") for (int _i = 0; _i < 2; ++_i) \
;         __builtin_amdgcn_global_load_lds((const unsigned*)((const char*)(gbase) + (voff)[_i]), (LAS unsigned*)(lds + (bufoff) + ldsw + _i * 8192), 16, 0, 0); } while (0)
; #define PG8_WAIT_V(n) asm volatile("s_waitcnt vmcnt(" #n ")" ::: "memory")
; #define PG8_BAR __builtin_amdgcn_s_barrier()
; template <class Epi>
; __device__ __forceinline__ void gemm_phase(LAS unsigned char* lds, const Gemm g, const StaticOrder& S, const Epi& E, const int tid) {
;     ...
;                 for (int n = 0; n < 2; ++n) acc[a][b][m][n] = (f32x4){0.f, 0.f, 0.f, 0.f};
;     bf16x8 At[4][2], B0[2][2], B1[2][2];
;     const char* cA = (const char*)g.A + (size_t)cur.pm * tstepA + (size_t)cur.pn * pnoffA; const char* cB = (const char*)g.Bt + (size_t)cur.pn * tstepB;
;     PG8_STAGE(PG8_SB(0, 0), cB, voffB); PG8_STAGE(PG8_SB(0, 1), cB + hstepB, voffB); PG8_STAGE(PG8_SA(0, 0), cA, voffA); PG8_STAGE(PG8_SA(0, 1), cA + hstepA, voffA);
;     if (wr == 1) PG8_BAR;
;     PG8_WAIT_V(2); PG8_BAR;
;     PG8_STAGE(PG8_SB(1, 0), cB + kstep, voffB); PG8_STAGE(PG8_SA(1, 0), cA + kstepA, voffA); PG8_STAGE(PG8_SB(1, 1), cB + hstepB + kstep, voffB);
;     PG8_WAIT_V(6); PG8_BAR;
;     for (;;) {
;         const bool has_next = S.next(ui + 1, nxt);
;         const char* nA = has_next ? (const char*)g.A + (size_t)nxt.pm * tstepA + (size_t)nxt.pn * pnoffA : cA; const char* nB = has_next ? (const char*)g.Bt + (size_t)nxt.pn * tstepB : cB;
;         for (int t = 0; t < nt; t += 2) {
;             const bool last = (t == nt - 2);
;             const char* a1 = cA + (size_t)(t + 1) * kstepA;
;             const char* a2 = last ? nA : cA + (size_t)(t + 2) * kstepA; const char* b2 = last ? nB : cB + (size_t)(t + 2) * kstep;
;             const char* a3 = a2 + kstepA; const char* b3 = b2 + kstep;
;             PG8_LDB(B0, 0, 0); PG8_LDB(B1, 0, 1); PG8_SCHED; PG8_LDA(At, 0, 0); PG8_STAGE(PG8_SA(1, 1), a1 + hstepA, voffA);
;             PG8_WAIT_V(8); PG8_WAIT_L(0); PG8_BAR; PG8_MMA(0, 0, At, B0); PG8_MMA(0, 1, At, B1); PG8_BAR; PG8_SCHED;
;             PG8_LDA(At, 0, 1); PG8_STAGE(PG8_SB(0, 0), b2, voffB); PG8_STAGE(PG8_SB(0, 1), b2 + hstepB, voffB); PG8_STAGE(PG8_SA(0, 0), a2, voffA);
;             PG8_WAIT_V(8); PG8_WAIT_L(0); PG8_BAR; PG8_MMA(1, 0, At, B0); PG8_MMA(1, 1, At, B1); PG8_BAR; PG8_SCHED;
.LBB0_224:
	s_ashr_i32 s11, s10, 31
	s_lshl_b64 s[12:13], s[10:11], 19
	s_add_u32 s12, s24, s12
	s_addc_u32 s13, s25, s13
	s_and_b64 s[14:15], s[4:5], exec
	s_cselect_b32 s11, s13, s17
	s_cselect_b32 s47, s12, s16
	s_ashr_i32 s9, s8, 31
	s_lshl_b64 s[14:15], s[8:9], 19
	s_add_u32 s14, s84, s14
	s_addc_u32 s15, s85, s15
	s_and_b64 s[34:35], s[4:5], exec
	s_cselect_b32 s9, s15, s29
	s_cselect_b32 s48, s14, s28
	s_add_u32 s49, s28, 0x100
	s_addc_u32 s50, s29, 0
	s_mov_b32 s51, -2
	s_add_u32 s28, s16, 0x1000
	s_addc_u32 s29, s17, 0
	s_add_i32 s52, 0, 0x10000
	s_cmp_eq_u32 s51, 12
	s_cselect_b32 s41, s11, s29
	s_cselect_b32 s40, s47, s28
	s_cselect_b32 s35, s9, s50
	s_cselect_b32 s34, s48, s49
	s_add_i32 s53, 0, 0x14000
	v_add_u32_e32 v140, s52, v175
	v_add_u32_e32 v164, s53, v175
	ds_read_b128 v[128:131], v140
	ds_read_b128 v[132:135], v140 offset:1024
	ds_read_b128 v[136:139], v140 offset:2048
	ds_read_b128 v[140:143], v140 offset:3072
	ds_read_b128 v[156:159], v164
	ds_read_b128 v[160:163], v164 offset:1024
	ds_read_b128 v[168:171], v164 offset:2048
	ds_read_b128 v[178:181], v164 offset:3072
	v_lshl_add_u64 v[164:165], s[16:17], 0, v[152:153]
	s_add_i32 m0, s21, 0xc000
	ds_read_b128 v[202:205], v196
	ds_read_b128 v[206:209], v196 offset:1024
	ds_read_b128 v[210:213], v196 offset:2048
	ds_read_b128 v[214:217], v196 offset:3072
	ds_read_b128 v[226:229], v196 offset:4096
	ds_read_b128 v[230:233], v196 offset:5120
	ds_read_b128 v[234:237], v196 offset:6144
	ds_read_b128 v[238:241], v196 offset:7168
	global_load_lds_dwordx4 v[164:165], off
	v_lshl_add_u64 v[164:165], s[16:17], 0, v[154:155]
	s_add_i32 m0, s21, 0xe000
	s_nop 0
	global_load_lds_dwordx4 v[164:165], off
	s_waitcnt vmcnt(8)
	s_waitcnt lgkmcnt(0)
	s_barrier
	v_mfma_f32_16x16x32_bf16 v[124:127], v[128:131], v[202:205], 0
	v_mfma_f32_16x16x32_bf16 v[120:123], v[136:139], v[202:205], 0
	v_mfma_f32_16x16x32_bf16 v[116:119], v[128:131], v[210:213], 0
	v_mfma_f32_16x16x32_bf16 v[108:111], v[136:139], v[210:213], 0
	v_mfma_f32_16x16x32_bf16 v[100:103], v[128:131], v[226:229], 0
	v_mfma_f32_16x16x32_bf16 v[92:95], v[136:139], v[226:229], 0
	v_mfma_f32_16x16x32_bf16 v[84:87], v[128:131], v[234:237], 0
	v_mfma_f32_16x16x32_bf16 v[76:79], v[136:139], v[234:237], 0
	v_mfma_f32_16x16x32_bf16 v[124:127], v[132:135], v[206:209], v[124:127]
	v_mfma_f32_16x16x32_bf16 v[120:123], v[140:143], v[206:209], v[120:123]
	v_mfma_f32_16x16x32_bf16 v[116:119], v[132:135], v[214:217], v[116:119]
	v_mfma_f32_16x16x32_bf16 v[108:111], v[140:143], v[214:217], v[108:111]
	v_mfma_f32_16x16x32_bf16 v[100:103], v[132:135], v[230:233], v[100:103]
	v_mfma_f32_16x16x32_bf16 v[92:95], v[140:143], v[230:233], v[92:95]
	v_mfma_f32_16x16x32_bf16 v[84:87], v[132:135], v[238:241], v[84:87]
	v_mfma_f32_16x16x32_bf16 v[76:79], v[140:143], v[238:241], v[76:79]
	v_mfma_f32_16x16x32_bf16 v[112:115], v[156:159], v[202:205], 0
	v_mfma_f32_16x16x32_bf16 v[104:107], v[168:171], v[202:205], 0
	v_mfma_f32_16x16x32_bf16 v[96:99], v[156:159], v[210:213], 0
	v_mfma_f32_16x16x32_bf16 v[88:91], v[168:171], v[210:213], 0
	v_mfma_f32_16x16x32_bf16 v[80:83], v[156:159], v[226:229], 0
	v_mfma_f32_16x16x32_bf16 v[72:75], v[168:171], v[226:229], 0
	v_mfma_f32_16x16x32_bf16 v[68:71], v[156:159], v[234:237], 0
	v_mfma_f32_16x16x32_bf16 v[64:67], v[168:171], v[234:237], 0
	v_mfma_f32_16x16x32_bf16 v[112:115], v[160:163], v[206:209], v[112:115]
	v_mfma_f32_16x16x32_bf16 v[104:107], v[178:181], v[206:209], v[104:107]
	v_mfma_f32_16x16x32_bf16 v[96:99], v[160:163], v[214:217], v[96:99]
	v_mfma_f32_16x16x32_bf16 v[88:91], v[178:181], v[214:217], v[88:91]
	v_mfma_f32_16x16x32_bf16 v[80:83], v[160:163], v[230:233], v[80:83]
	v_mfma_f32_16x16x32_bf16 v[72:75], v[178:181], v[230:233], v[72:75]
	v_mfma_f32_16x16x32_bf16 v[68:71], v[160:163], v[238:241], v[68:71]
	v_mfma_f32_16x16x32_bf16 v[64:67], v[178:181], v[238:241], v[64:67]
	s_barrier
	s_add_i32 s16, s52, s20
	v_lshl_add_u64 v[164:165], s[34:35], 0, v[176:177]
	s_mov_b32 m0, s16
	ds_read_b128 v[202:205], v196 offset:16384
	ds_read_b128 v[206:209], v196 offset:17408
	ds_read_b128 v[210:213], v196 offset:18432
	ds_read_b128 v[214:217], v196 offset:19456
	ds_read_b128 v[226:229], v196 offset:20480
	ds_read_b128 v[230:233], v196 offset:21504
	ds_read_b128 v[234:237], v196 offset:22528
	ds_read_b128 v[238:241], v196 offset:23552
	global_load_lds_dwordx4 v[164:165], off
	s_add_i32 m0, s16, 0x2000
	s_add_u32 s16, s34, 0x40000
	v_lshl_add_u64 v[172:173], s[34:35], 0, v[144:145]
	s_addc_u32 s17, s35, 0
	s_add_i32 s52, s53, s20
	global_load_lds_dwordx4 v[172:173], off
	v_lshl_add_u64 v[194:195], s[16:17], 0, v[176:177]
	s_mov_b32 m0, s52
	v_lshl_add_u64 v[198:199], s[40:41], 0, v[146:147]
	global_load_lds_dwordx4 v[194:195], off
	v_lshl_add_u64 v[194:195], s[16:17], 0, v[144:145]
	s_add_i32 m0, s52, 0x2000
	s_nop 0
	global_load_lds_dwordx4 v[194:195], off
	v_lshl_add_u64 v[194:195], s[40:41], 0, v[148:149]
	s_mov_b32 m0, s21
	s_nop 0
	global_load_lds_dwordx4 v[194:195], off
	s_mov_b32 m0, s22
	s_nop 0
	global_load_lds_dwordx4 v[198:199], off
	s_waitcnt vmcnt(8)
	s_waitcnt lgkmcnt(0)
	s_barrier
; #define PG8_STAGE(bufoff, gbase, voff) do { _Pragma("unroll") for (int _i = 0; _i < 2; ++_i) \
;         __builtin_amdgcn_global_load_lds((const unsigned*)((const char*)(gbase) + (voff)[_i]), (LAS unsigned*)(lds + (bufoff) + ldsw + _i * 8192), 16, 0, 0); } while (0)
; #define PG8_LDA(dst, b, h) do { _Pragma("unroll") for (int m = 0; m < 4; ++m) _Pragma("unroll") for (int k = 0; k < 2; ++k) dst[m][k] = *(const LAS bf16x8*)(lds + PG8_SA(b, h) + aoff + m * 2048 + k * 1024); } while (0)
; #define PG8_LDB(dst, b, h) do { _Pragma("unroll") for (int n = 0; n < 2; ++n) _Pragma("unroll") for (int k = 0; k < 2; ++k) dst[n][k] = *(const LAS bf16x8*)(lds + PG8_SB(b, h) + boff + n * 2048 + k * 1024); } while (0)
; #define PG8_MMA(ai, bj, At, Bt) do { __builtin_amdgcn_s_setprio(1); _Pragma("unroll") for (int m = 0; m < 4; ++m) _Pragma("unroll") for (int n = 0; n < 2; ++n) _Pragma("unroll") for (int k = 0; k < 2; ++k) \
;         acc[ai][bj][m][n] = __builtin_amdgcn_mfma_f32_16x16x32_bf16(Bt[n][k], At[m][k], acc[ai][bj][m][n], 0, 0, 0); __builtin_amdgcn_s_setprio(0); } while (0)
; #define PG8_WAIT_V(n) asm volatile("s_waitcnt vmcnt(" #n ")" ::: "memory")
; #define PG8_WAIT_L(n) asm volatile("s_waitcnt lgkmcnt(" #n ")" ::: "memory")
; #define PG8_BAR __builtin_amdgcn_s_barrier()
; #define PG8_SCHED __builtin_amdgcn_sched_barrier(0)
; template <class Epi>
; __device__ __forceinline__ void gemm_phase(LAS unsigned char* lds, const Gemm g, const StaticOrder& S, const Epi& E, const int tid) {
;     ...
;             PG8_WAIT_V(8); PG8_WAIT_L(0); PG8_BAR; PG8_MMA(1, 0, At, B0); PG8_MMA(1, 1, At, B1); PG8_BAR; PG8_SCHED;
;             PG8_LDB(B0, 1, 0); PG8_LDB(B1, 1, 1); PG8_SCHED; PG8_LDA(At, 1, 0); PG8_STAGE(PG8_SA(0, 1), a2 + hstepA, voffA);
;             PG8_WAIT_V(8); PG8_WAIT_L(0); PG8_BAR; PG8_MMA(0, 0, At, B0); PG8_MMA(0, 1, At, B1); PG8_BAR; PG8_SCHED;
;             PG8_LDA(At, 1, 1); PG8_STAGE(PG8_SB(1, 0), b3, voffB); PG8_STAGE(PG8_SB(1, 1), b3 + hstepB, voffB); PG8_STAGE(PG8_SA(1, 0), a3, voffA);
	v_mfma_f32_16x16x32_bf16 v[60:63], v[128:131], v[202:205], 0
	v_mfma_f32_16x16x32_bf16 v[56:59], v[136:139], v[202:205], 0
	v_mfma_f32_16x16x32_bf16 v[52:55], v[128:131], v[210:213], 0
	v_mfma_f32_16x16x32_bf16 v[44:47], v[136:139], v[210:213], 0
	v_mfma_f32_16x16x32_bf16 v[36:39], v[128:131], v[226:229], 0
	v_mfma_f32_16x16x32_bf16 v[28:31], v[136:139], v[226:229], 0
	v_mfma_f32_16x16x32_bf16 v[20:23], v[128:131], v[234:237], 0
	v_mfma_f32_16x16x32_bf16 v[12:15], v[136:139], v[234:237], 0
	v_mfma_f32_16x16x32_bf16 v[60:63], v[132:135], v[206:209], v[60:63]
	v_mfma_f32_16x16x32_bf16 v[56:59], v[140:143], v[206:209], v[56:59]
	v_mfma_f32_16x16x32_bf16 v[52:55], v[132:135], v[214:217], v[52:55]
	v_mfma_f32_16x16x32_bf16 v[44:47], v[140:143], v[214:217], v[44:47]
	v_mfma_f32_16x16x32_bf16 v[36:39], v[132:135], v[230:233], v[36:39]
	v_mfma_f32_16x16x32_bf16 v[28:31], v[140:143], v[230:233], v[28:31]
	v_mfma_f32_16x16x32_bf16 v[20:23], v[132:135], v[238:241], v[20:23]
	v_mfma_f32_16x16x32_bf16 v[12:15], v[140:143], v[238:241], v[12:15]
	v_mfma_f32_16x16x32_bf16 v[48:51], v[156:159], v[202:205], 0
	v_mfma_f32_16x16x32_bf16 v[40:43], v[168:171], v[202:205], 0
	v_mfma_f32_16x16x32_bf16 v[32:35], v[156:159], v[210:213], 0
	v_mfma_f32_16x16x32_bf16 v[24:27], v[168:171], v[210:213], 0
	v_mfma_f32_16x16x32_bf16 v[16:19], v[156:159], v[226:229], 0
	v_mfma_f32_16x16x32_bf16 v[8:11], v[168:171], v[226:229], 0
	v_mfma_f32_16x16x32_bf16 v[4:7], v[156:159], v[234:237], 0
	v_mfma_f32_16x16x32_bf16 v[0:3], v[168:171], v[234:237], 0
	v_mfma_f32_16x16x32_bf16 v[48:51], v[160:163], v[206:209], v[48:51]
	v_mfma_f32_16x16x32_bf16 v[40:43], v[178:181], v[206:209], v[40:43]
	v_mfma_f32_16x16x32_bf16 v[32:35], v[160:163], v[214:217], v[32:35]
	v_mfma_f32_16x16x32_bf16 v[24:27], v[178:181], v[214:217], v[24:27]
	v_mfma_f32_16x16x32_bf16 v[16:19], v[160:163], v[230:233], v[16:19]
	v_mfma_f32_16x16x32_bf16 v[8:11], v[178:181], v[230:233], v[8:11]
	v_mfma_f32_16x16x32_bf16 v[4:7], v[160:163], v[238:241], v[4:7]
	v_mfma_f32_16x16x32_bf16 v[0:3], v[178:181], v[238:241], v[0:3]
	s_barrier
	s_add_i32 s52, 0, 0x18000
	s_add_i32 s53, 0, 0x1c000
	v_add_u32_e32 v140, s52, v175
	v_add_u32_e32 v166, s53, v175
	ds_read_b128 v[128:131], v140
	ds_read_b128 v[132:135], v140 offset:1024
	ds_read_b128 v[136:139], v140 offset:2048
	ds_read_b128 v[140:143], v140 offset:3072
	ds_read_b128 v[156:159], v166
	ds_read_b128 v[160:163], v166 offset:1024
	ds_read_b128 v[168:171], v166 offset:2048
	ds_read_b128 v[178:181], v166 offset:3072
	s_add_u32 s16, s40, 0x40000
	s_addc_u32 s17, s41, 0
	s_mov_b32 m0, s23
	v_lshl_add_u64 v[218:219], s[16:17], 0, v[148:149]
	ds_read_b128 v[202:205], v196 offset:32768
	ds_read_b128 v[206:209], v196 offset:33792
	ds_read_b128 v[210:213], v196 offset:34816
	ds_read_b128 v[214:217], v196 offset:35840
	ds_read_b128 v[226:229], v196 offset:36864
	ds_read_b128 v[230:233], v196 offset:37888
	ds_read_b128 v[234:237], v196 offset:38912
	ds_read_b128 v[238:241], v196 offset:39936
	global_load_lds_dwordx4 v[218:219], off
	v_lshl_add_u64 v[218:219], s[16:17], 0, v[146:147]
	s_mov_b32 m0, s30
	s_nop 0
	global_load_lds_dwordx4 v[218:219], off
	s_waitcnt vmcnt(8)
	s_waitcnt lgkmcnt(0)
	s_barrier
	v_mfma_f32_16x16x32_bf16 v[124:127], v[128:131], v[202:205], v[124:127]
	v_mfma_f32_16x16x32_bf16 v[120:123], v[136:139], v[202:205], v[120:123]
	v_mfma_f32_16x16x32_bf16 v[116:119], v[128:131], v[210:213], v[116:119]
	v_mfma_f32_16x16x32_bf16 v[108:111], v[136:139], v[210:213], v[108:111]
	v_mfma_f32_16x16x32_bf16 v[100:103], v[128:131], v[226:229], v[100:103]
	v_mfma_f32_16x16x32_bf16 v[92:95], v[136:139], v[226:229], v[92:95]
	v_mfma_f32_16x16x32_bf16 v[84:87], v[128:131], v[234:237], v[84:87]
	v_mfma_f32_16x16x32_bf16 v[76:79], v[136:139], v[234:237], v[76:79]
	v_mfma_f32_16x16x32_bf16 v[124:127], v[132:135], v[206:209], v[124:127]
	v_mfma_f32_16x16x32_bf16 v[120:123], v[140:143], v[206:209], v[120:123]
	v_mfma_f32_16x16x32_bf16 v[116:119], v[132:135], v[214:217], v[116:119]
	v_mfma_f32_16x16x32_bf16 v[108:111], v[140:143], v[214:217], v[108:111]
	v_mfma_f32_16x16x32_bf16 v[100:103], v[132:135], v[230:233], v[100:103]
	v_mfma_f32_16x16x32_bf16 v[92:95], v[140:143], v[230:233], v[92:95]
	v_mfma_f32_16x16x32_bf16 v[84:87], v[132:135], v[238:241], v[84:87]
	v_mfma_f32_16x16x32_bf16 v[76:79], v[140:143], v[238:241], v[76:79]
	v_mfma_f32_16x16x32_bf16 v[112:115], v[156:159], v[202:205], v[112:115]
	v_mfma_f32_16x16x32_bf16 v[104:107], v[168:171], v[202:205], v[104:107]
	v_mfma_f32_16x16x32_bf16 v[96:99], v[156:159], v[210:213], v[96:99]
	v_mfma_f32_16x16x32_bf16 v[88:91], v[168:171], v[210:213], v[88:91]
	v_mfma_f32_16x16x32_bf16 v[80:83], v[156:159], v[226:229], v[80:83]
	v_mfma_f32_16x16x32_bf16 v[72:75], v[168:171], v[226:229], v[72:75]
	v_mfma_f32_16x16x32_bf16 v[68:71], v[156:159], v[234:237], v[68:71]
	v_mfma_f32_16x16x32_bf16 v[64:67], v[168:171], v[234:237], v[64:67]
	v_mfma_f32_16x16x32_bf16 v[112:115], v[160:163], v[206:209], v[112:115]
	v_mfma_f32_16x16x32_bf16 v[104:107], v[178:181], v[206:209], v[104:107]
	v_mfma_f32_16x16x32_bf16 v[96:99], v[160:163], v[214:217], v[96:99]
	v_mfma_f32_16x16x32_bf16 v[88:91], v[178:181], v[214:217], v[88:91]
	v_mfma_f32_16x16x32_bf16 v[80:83], v[160:163], v[230:233], v[80:83]
	v_mfma_f32_16x16x32_bf16 v[72:75], v[178:181], v[230:233], v[72:75]
	v_mfma_f32_16x16x32_bf16 v[68:71], v[160:163], v[238:241], v[68:71]
	v_mfma_f32_16x16x32_bf16 v[64:67], v[178:181], v[238:241], v[64:67]
	s_barrier
; #define PG8_STAGE(bufoff, gbase, voff) do { _Pragma("unroll") for (int _i = 0; _i < 2; ++_i) \
;         __builtin_amdgcn_global_load_lds((const unsigned*)((const char*)(gbase) + (voff)[_i]), (LAS unsigned*)(lds + (bufoff) + ldsw + _i * 8192), 16, 0, 0); } while (0)
; #define PG8_LDA(dst, b, h) do { _Pragma("unroll") for (int m = 0; m < 4; ++m) _Pragma("unroll") for (int k = 0; k < 2; ++k) dst[m][k] = *(const LAS bf16x8*)(lds + PG8_SA(b, h) + aoff + m * 2048 + k * 1024); } while (0)
; #define PG8_MMA(ai, bj, At, Bt) do { __builtin_amdgcn_s_setprio(1); _Pragma("unroll") for (int m = 0; m < 4; ++m) _Pragma("unroll") for (int n = 0; n < 2; ++n) _Pragma("unroll") for (int k = 0; k < 2; ++k) \
;         acc[ai][bj][m][n] = __builtin_amdgcn_mfma_f32_16x16x32_bf16(Bt[n][k], At[m][k], acc[ai][bj][m][n], 0, 0, 0); __builtin_amdgcn_s_setprio(0); } while (0)
; #define PG8_WAIT_V(n) asm volatile("s_waitcnt vmcnt(" #n ")" ::: "memory")
; #define PG8_WAIT_L(n) asm volatile("s_waitcnt lgkmcnt(" #n ")" ::: "memory")
; #define PG8_BAR __builtin_amdgcn_s_barrier()
; #define PG8_SCHED __builtin_amdgcn_sched_barrier(0)
; template <class Epi>
; __device__ __forceinline__ void gemm_phase(LAS unsigned char* lds, const Gemm g, const StaticOrder& S, const Epi& E, const int tid) {
;     ...
;             PG8_LDA(At, 1, 1); PG8_STAGE(PG8_SB(1, 0), b3, voffB); PG8_STAGE(PG8_SB(1, 1), b3 + hstepB, voffB); PG8_STAGE(PG8_SA(1, 0), a3, voffA);
;             PG8_WAIT_V(8); PG8_WAIT_L(0); PG8_BAR; PG8_MMA(1, 0, At, B0); PG8_MMA(1, 1, At, B1); PG8_BAR; PG8_SCHED;
;         }
	s_add_i32 s16, s52, s20
	v_lshl_add_u64 v[164:165], v[164:165], 0, s[36:37]
	s_mov_b32 m0, s16
	ds_read_b128 v[202:205], v196 offset:49152
	ds_read_b128 v[206:209], v196 offset:50176
	ds_read_b128 v[210:213], v196 offset:51200
	ds_read_b128 v[214:217], v196 offset:52224
	ds_read_b128 v[226:229], v196 offset:53248
	ds_read_b128 v[230:233], v196 offset:54272
	ds_read_b128 v[234:237], v196 offset:55296
	ds_read_b128 v[238:241], v196 offset:56320
	global_load_lds_dwordx4 v[164:165], off
	s_add_i32 m0, s16, 0x2000
	s_add_u32 s16, s34, 0x40080
	v_lshl_add_u64 v[164:165], v[172:173], 0, s[36:37]
	s_addc_u32 s17, s35, 0
	s_add_i32 s34, s53, s20
	global_load_lds_dwordx4 v[164:165], off
	v_lshl_add_u64 v[164:165], s[16:17], 0, v[176:177]
	s_mov_b32 m0, s34
	s_nop 0
	global_load_lds_dwordx4 v[164:165], off
	v_lshl_add_u64 v[164:165], s[16:17], 0, v[144:145]
	s_add_i32 m0, s34, 0x2000
	s_nop 0
	global_load_lds_dwordx4 v[164:165], off
	v_lshl_add_u64 v[164:165], v[194:195], 0, s[76:77]
	s_mov_b32 m0, s42
	s_nop 0
	global_load_lds_dwordx4 v[164:165], off
	v_lshl_add_u64 v[164:165], v[198:199], 0, s[76:77]
	s_mov_b32 m0, s43
	s_nop 0
	global_load_lds_dwordx4 v[164:165], off
	s_waitcnt vmcnt(8)
	s_waitcnt lgkmcnt(0)
	s_barrier
	v_mfma_f32_16x16x32_bf16 v[60:63], v[128:131], v[202:205], v[60:63]
	v_mfma_f32_16x16x32_bf16 v[56:59], v[136:139], v[202:205], v[56:59]
	v_mfma_f32_16x16x32_bf16 v[52:55], v[128:131], v[210:213], v[52:55]
	v_mfma_f32_16x16x32_bf16 v[44:47], v[136:139], v[210:213], v[44:47]
	v_mfma_f32_16x16x32_bf16 v[36:39], v[128:131], v[226:229], v[36:39]
	v_mfma_f32_16x16x32_bf16 v[28:31], v[136:139], v[226:229], v[28:31]
	v_mfma_f32_16x16x32_bf16 v[20:23], v[128:131], v[234:237], v[20:23]
	v_mfma_f32_16x16x32_bf16 v[12:15], v[136:139], v[234:237], v[12:15]
	v_mfma_f32_16x16x32_bf16 v[60:63], v[132:135], v[206:209], v[60:63]
	v_mfma_f32_16x16x32_bf16 v[56:59], v[140:143], v[206:209], v[56:59]
	v_mfma_f32_16x16x32_bf16 v[52:55], v[132:135], v[214:217], v[52:55]
	v_mfma_f32_16x16x32_bf16 v[44:47], v[140:143], v[214:217], v[44:47]
	v_mfma_f32_16x16x32_bf16 v[36:39], v[132:135], v[230:233], v[36:39]
	v_mfma_f32_16x16x32_bf16 v[28:31], v[140:143], v[230:233], v[28:31]
	v_mfma_f32_16x16x32_bf16 v[20:23], v[132:135], v[238:241], v[20:23]
	v_mfma_f32_16x16x32_bf16 v[12:15], v[140:143], v[238:241], v[12:15]
	v_mfma_f32_16x16x32_bf16 v[48:51], v[156:159], v[202:205], v[48:51]
	v_mfma_f32_16x16x32_bf16 v[40:43], v[168:171], v[202:205], v[40:43]
	v_mfma_f32_16x16x32_bf16 v[32:35], v[156:159], v[210:213], v[32:35]
	v_mfma_f32_16x16x32_bf16 v[24:27], v[168:171], v[210:213], v[24:27]
	v_mfma_f32_16x16x32_bf16 v[16:19], v[156:159], v[226:229], v[16:19]
	v_mfma_f32_16x16x32_bf16 v[8:11], v[168:171], v[226:229], v[8:11]
	v_mfma_f32_16x16x32_bf16 v[4:7], v[156:159], v[234:237], v[4:7]
	v_mfma_f32_16x16x32_bf16 v[0:3], v[168:171], v[234:237], v[0:3]
	v_mfma_f32_16x16x32_bf16 v[48:51], v[160:163], v[206:209], v[48:51]
	v_mfma_f32_16x16x32_bf16 v[40:43], v[178:181], v[206:209], v[40:43]
	v_mfma_f32_16x16x32_bf16 v[32:35], v[160:163], v[214:217], v[32:35]
	v_mfma_f32_16x16x32_bf16 v[24:27], v[178:181], v[214:217], v[24:27]
	v_mfma_f32_16x16x32_bf16 v[16:19], v[160:163], v[230:233], v[16:19]
	v_mfma_f32_16x16x32_bf16 v[8:11], v[178:181], v[230:233], v[8:11]
	v_mfma_f32_16x16x32_bf16 v[4:7], v[160:163], v[238:241], v[4:7]
	v_mfma_f32_16x16x32_bf16 v[0:3], v[178:181], v[238:241], v[0:3]
	s_barrier
	s_add_i32 s51, s51, 2
	s_add_u32 s49, s49, 0x100
	s_addc_u32 s50, s50, 0
	s_mov_b64 s[16:17], s[28:29]

; #define PG8_STAGE(bufoff, gbase, voff) do { _Pragma("unroll") for (int _i = 0; _i < 2; ++_i) \
;         __builtin_amdgcn_global_load_lds((const unsigned*)((const char*)(gbase) + (voff)[_i]), (LAS unsigned*)(lds + (bufoff) + ldsw + _i * 8192), 16, 0, 0); } while (0)
; #define PG8_WAIT_V(n) asm volatile("s_waitcnt vmcnt(" #n ")" ::: "memory")
; #define PG8_BAR __builtin_amdgcn_s_barrier()
; template <class Epi>
; __device__ __forceinline__ void gemm_phase(LAS unsigned char* lds, const Gemm g, const StaticOrder& S, const Epi& E, const int tid) {
;     ...
;                 for (int n = 0; n < 2; ++n) acc[a][b][m][n] = (f32x4){0.f, 0.f, 0.f, 0.f};
;     bf16x8 At[4][2], B0[2][2], B1[2][2];
;     const char* cA = (const char*)g.A + (size_t)cur.pm * tstepA + (size_t)cur.pn * pnoffA; const char* cB = (const char*)g.Bt + (size_t)cur.pn * tstepB;
;     PG8_STAGE(PG8_SB(0, 0), cB, voffB); PG8_STAGE(PG8_SB(0, 1), cB + hstepB, voffB); PG8_STAGE(PG8_SA(0, 0), cA, voffA); PG8_STAGE(PG8_SA(0, 1), cA + hstepA, voffA);
;     if (wr == 1) PG8_BAR;
;     PG8_WAIT_V(2); PG8_BAR;
;     PG8_STAGE(PG8_SB(1, 0), cB + kstep, voffB); PG8_STAGE(PG8_SA(1, 0), cA + kstepA, voffA); PG8_STAGE(PG8_SB(1, 1), cB + hstepB + kstep, voffB);
;     PG8_WAIT_V(6); PG8_BAR;
;     for (;;) {
;         const bool has_next = S.next(ui + 1, nxt);
;         const char* nA = has_next ? (const char*)g.A + (size_t)nxt.pm * tstepA + (size_t)nxt.pn * pnoffA : cA; const char* nB = has_next ? (const char*)g.Bt + (size_t)nxt.pn * tstepB : cB;
;         for (int t = 0; t < nt; t += 2) {
;             const bool last = (t == nt - 2);
;             const char* a1 = cA + (size_t)(t + 1) * kstepA;
;             const char* a2 = last ? nA : cA + (size_t)(t + 2) * kstepA; const char* b2 = last ? nB : cB + (size_t)(t + 2) * kstep;
;             const char* a3 = a2 + kstepA; const char* b3 = b2 + kstep;
;             PG8_LDB(B0, 0, 0); PG8_LDB(B1, 0, 1); PG8_SCHED; PG8_LDA(At, 0, 0); PG8_STAGE(PG8_SA(1, 1), a1 + hstepA, voffA);
;             PG8_WAIT_V(8); PG8_WAIT_L(0); PG8_BAR; PG8_MMA(0, 0, At, B0); PG8_MMA(0, 1, At, B1); PG8_BAR; PG8_SCHED;
;             PG8_LDA(At, 0, 1); PG8_STAGE(PG8_SB(0, 0), b2, voffB); PG8_STAGE(PG8_SB(0, 1), b2 + hstepB, voffB); PG8_STAGE(PG8_SA(0, 0), a2, voffA);
;             PG8_WAIT_V(8); PG8_WAIT_L(0); PG8_BAR; PG8_MMA(1, 0, At, B0); PG8_MMA(1, 1, At, B1); PG8_BAR; PG8_SCHED;
.LBB0_338:
	s_ashr_i32 s15, s14, 31
	s_lshl_b64 s[2:3], s[14:15], 19
	s_add_u32 s16, s24, s2
	s_addc_u32 s17, s25, s3
	s_and_b64 s[2:3], s[4:5], exec
	s_cselect_b32 s15, s17, s29
	s_cselect_b32 s51, s16, s28
	s_ashr_i32 s13, s12, 31
	s_lshl_b64 s[2:3], s[12:13], 19
	s_add_u32 s2, s20, s2
	s_addc_u32 s3, s21, s3
	s_and_b64 s[40:41], s[4:5], exec
	s_cselect_b32 s13, s3, s35
	s_cselect_b32 s52, s2, s34
	s_add_u32 s53, s34, 0x100
	s_addc_u32 s54, s35, 0
	s_mov_b32 s55, -2
	s_add_u32 s34, s28, 0x1000
	s_addc_u32 s35, s29, 0
	s_add_i32 s56, 0, 0x10000
	s_cmp_eq_u32 s55, 12
	s_cselect_b32 s43, s15, s35
	s_cselect_b32 s42, s51, s34
	v_add_u32_e32 v142, s56, v145
	s_cselect_b32 s41, s13, s54
	s_cselect_b32 s40, s52, s53
	s_add_i32 s57, 0, 0x14000
	ds_read_b128 v[158:161], v142
	ds_read_b128 v[162:165], v142 offset:1024
	ds_read_b128 v[166:169], v142 offset:2048
	ds_read_b128 v[170:173], v142 offset:3072
	v_add_u32_e32 v142, s57, v145
	ds_read_b128 v[194:197], v142
	ds_read_b128 v[202:205], v142 offset:1024
	ds_read_b128 v[206:209], v142 offset:2048
	ds_read_b128 v[210:213], v142 offset:3072
	v_lshl_add_u64 v[146:147], s[28:29], 0, v[138:139]
	s_add_i32 m0, s23, 0xc000
	ds_read_b128 v[214:217], v157
	ds_read_b128 v[226:229], v157 offset:1024
	ds_read_b128 v[230:233], v157 offset:2048
	ds_read_b128 v[234:237], v157 offset:3072
	ds_read_b128 v[238:241], v157 offset:4096
	ds_read_b128 v[242:245], v157 offset:5120
	ds_read_b128 v[246:249], v157 offset:6144
	ds_read_b128 v[178:181], v157 offset:7168
	global_load_lds_dwordx4 v[146:147], off
	v_lshl_add_u64 v[146:147], s[28:29], 0, v[140:141]
	s_add_i32 m0, s23, 0xe000
	s_nop 0
	global_load_lds_dwordx4 v[146:147], off
	s_waitcnt vmcnt(8)
	s_waitcnt lgkmcnt(0)
	s_barrier
	v_mfma_f32_16x16x32_bf16 v[124:127], v[158:161], v[214:217], 0
	v_mfma_f32_16x16x32_bf16 v[120:123], v[166:169], v[214:217], 0
	v_mfma_f32_16x16x32_bf16 v[116:119], v[158:161], v[230:233], 0
	v_mfma_f32_16x16x32_bf16 v[108:111], v[166:169], v[230:233], 0
	v_mfma_f32_16x16x32_bf16 v[100:103], v[158:161], v[238:241], 0
	v_mfma_f32_16x16x32_bf16 v[92:95], v[166:169], v[238:241], 0
	v_mfma_f32_16x16x32_bf16 v[84:87], v[158:161], v[246:249], 0
	v_mfma_f32_16x16x32_bf16 v[76:79], v[166:169], v[246:249], 0
	v_mfma_f32_16x16x32_bf16 v[124:127], v[162:165], v[226:229], v[124:127]
	v_mfma_f32_16x16x32_bf16 v[120:123], v[170:173], v[226:229], v[120:123]
	v_mfma_f32_16x16x32_bf16 v[116:119], v[162:165], v[234:237], v[116:119]
	v_mfma_f32_16x16x32_bf16 v[108:111], v[170:173], v[234:237], v[108:111]
	v_mfma_f32_16x16x32_bf16 v[100:103], v[162:165], v[242:245], v[100:103]
	v_mfma_f32_16x16x32_bf16 v[92:95], v[170:173], v[242:245], v[92:95]
	v_mfma_f32_16x16x32_bf16 v[84:87], v[162:165], v[178:181], v[84:87]
	v_mfma_f32_16x16x32_bf16 v[76:79], v[170:173], v[178:181], v[76:79]
	v_mfma_f32_16x16x32_bf16 v[112:115], v[194:197], v[214:217], 0
	v_mfma_f32_16x16x32_bf16 v[104:107], v[206:209], v[214:217], 0
	v_mfma_f32_16x16x32_bf16 v[96:99], v[194:197], v[230:233], 0
	v_mfma_f32_16x16x32_bf16 v[88:91], v[206:209], v[230:233], 0
	v_mfma_f32_16x16x32_bf16 v[80:83], v[194:197], v[238:241], 0
	v_mfma_f32_16x16x32_bf16 v[72:75], v[206:209], v[238:241], 0
	v_mfma_f32_16x16x32_bf16 v[68:71], v[194:197], v[246:249], 0
	v_mfma_f32_16x16x32_bf16 v[64:67], v[206:209], v[246:249], 0
	v_mfma_f32_16x16x32_bf16 v[112:115], v[202:205], v[226:229], v[112:115]
	v_mfma_f32_16x16x32_bf16 v[104:107], v[210:213], v[226:229], v[104:107]
	v_mfma_f32_16x16x32_bf16 v[96:99], v[202:205], v[234:237], v[96:99]
	v_mfma_f32_16x16x32_bf16 v[88:91], v[210:213], v[234:237], v[88:91]
	v_mfma_f32_16x16x32_bf16 v[80:83], v[202:205], v[242:245], v[80:83]
	v_mfma_f32_16x16x32_bf16 v[72:75], v[210:213], v[242:245], v[72:75]
	v_mfma_f32_16x16x32_bf16 v[68:71], v[202:205], v[178:181], v[68:71]
	v_mfma_f32_16x16x32_bf16 v[64:67], v[210:213], v[178:181], v[64:67]
	s_barrier
	s_add_i32 s28, s56, s22
	v_lshl_add_u64 v[146:147], s[40:41], 0, v[132:133]
	s_mov_b32 m0, s28
	ds_read_b128 v[178:181], v157 offset:16384
	ds_read_b128 v[214:217], v157 offset:17408
	ds_read_b128 v[226:229], v157 offset:18432
	ds_read_b128 v[230:233], v157 offset:19456
	ds_read_b128 v[234:237], v157 offset:20480
	ds_read_b128 v[238:241], v157 offset:21504
	ds_read_b128 v[242:245], v157 offset:22528
	ds_read_b128 v[246:249], v157 offset:23552
	global_load_lds_dwordx4 v[146:147], off
	s_add_i32 m0, s28, 0x2000
	s_add_u32 s28, s40, 0x40000
	v_lshl_add_u64 v[150:151], s[40:41], 0, v[128:129]
	s_addc_u32 s29, s41, 0
	s_add_i32 s56, s57, s22
	global_load_lds_dwordx4 v[150:151], off
	v_lshl_add_u64 v[154:155], s[28:29], 0, v[132:133]
	s_mov_b32 m0, s56
	v_lshl_add_u64 v[174:175], s[42:43], 0, v[130:131]
	global_load_lds_dwordx4 v[154:155], off
	v_lshl_add_u64 v[154:155], s[28:29], 0, v[128:129]
	s_add_i32 m0, s56, 0x2000
	s_nop 0
	global_load_lds_dwordx4 v[154:155], off
	v_lshl_add_u64 v[154:155], s[42:43], 0, v[134:135]
	s_mov_b32 m0, s23
	s_nop 0
	global_load_lds_dwordx4 v[154:155], off
	s_mov_b32 m0, s30
	s_nop 0
	global_load_lds_dwordx4 v[174:175], off
	s_waitcnt vmcnt(8)
	s_waitcnt lgkmcnt(0)
	s_barrier
; #define PG8_STAGE(bufoff, gbase, voff) do { _Pragma("unroll") for (int _i = 0; _i < 2; ++_i) \
;         __builtin_amdgcn_global_load_lds((const unsigned*)((const char*)(gbase) + (voff)[_i]), (LAS unsigned*)(lds + (bufoff) + ldsw + _i * 8192), 16, 0, 0); } while (0)
; #define PG8_LDA(dst, b, h) do { _Pragma("unroll") for (int m = 0; m < 4; ++m) _Pragma("unroll") for (int k = 0; k < 2; ++k) dst[m][k] = *(const LAS bf16x8*)(lds + PG8_SA(b, h) + aoff + m * 2048 + k * 1024); } while (0)
; #define PG8_LDB(dst, b, h) do { _Pragma("unroll") for (int n = 0; n < 2; ++n) _Pragma("unroll") for (int k = 0; k < 2; ++k) dst[n][k] = *(const LAS bf16x8*)(lds + PG8_SB(b, h) + boff + n * 2048 + k * 1024); } while (0)
; #define PG8_MMA(ai, bj, At, Bt) do { __builtin_amdgcn_s_setprio(1); _Pragma("unroll") for (int m = 0; m < 4; ++m) _Pragma("unroll") for (int n = 0; n < 2; ++n) _Pragma("unroll") for (int k = 0; k < 2; ++k) \
;         acc[ai][bj][m][n] = __builtin_amdgcn_mfma_f32_16x16x32_bf16(Bt[n][k], At[m][k], acc[ai][bj][m][n], 0, 0, 0); __builtin_amdgcn_s_setprio(0); } while (0)
; #define PG8_WAIT_V(n) asm volatile("s_waitcnt vmcnt(" #n ")" ::: "memory")
; #define PG8_WAIT_L(n) asm volatile("s_waitcnt lgkmcnt(" #n ")" ::: "memory")
; #define PG8_BAR __builtin_amdgcn_s_barrier()
; #define PG8_SCHED __builtin_amdgcn_sched_barrier(0)
; template <class Epi>
; __device__ __forceinline__ void gemm_phase(LAS unsigned char* lds, const Gemm g, const StaticOrder& S, const Epi& E, const int tid) {
;     ...
;             PG8_WAIT_V(8); PG8_WAIT_L(0); PG8_BAR; PG8_MMA(1, 0, At, B0); PG8_MMA(1, 1, At, B1); PG8_BAR; PG8_SCHED;
;             PG8_LDB(B0, 1, 0); PG8_LDB(B1, 1, 1); PG8_SCHED; PG8_LDA(At, 1, 0); PG8_STAGE(PG8_SA(0, 1), a2 + hstepA, voffA);
;             PG8_WAIT_V(8); PG8_WAIT_L(0); PG8_BAR; PG8_MMA(0, 0, At, B0); PG8_MMA(0, 1, At, B1); PG8_BAR; PG8_SCHED;
;             PG8_LDA(At, 1, 1); PG8_STAGE(PG8_SB(1, 0), b3, voffB); PG8_STAGE(PG8_SB(1, 1), b3 + hstepB, voffB); PG8_STAGE(PG8_SA(1, 0), a3, voffA);
	v_mfma_f32_16x16x32_bf16 v[60:63], v[158:161], v[178:181], 0
	v_mfma_f32_16x16x32_bf16 v[56:59], v[166:169], v[178:181], 0
	v_mfma_f32_16x16x32_bf16 v[52:55], v[158:161], v[226:229], 0
	v_mfma_f32_16x16x32_bf16 v[44:47], v[166:169], v[226:229], 0
	v_mfma_f32_16x16x32_bf16 v[36:39], v[158:161], v[234:237], 0
	v_mfma_f32_16x16x32_bf16 v[28:31], v[166:169], v[234:237], 0
	v_mfma_f32_16x16x32_bf16 v[20:23], v[158:161], v[242:245], 0
	v_mfma_f32_16x16x32_bf16 v[12:15], v[166:169], v[242:245], 0
	v_mfma_f32_16x16x32_bf16 v[60:63], v[162:165], v[214:217], v[60:63]
	v_mfma_f32_16x16x32_bf16 v[56:59], v[170:173], v[214:217], v[56:59]
	v_mfma_f32_16x16x32_bf16 v[52:55], v[162:165], v[230:233], v[52:55]
	v_mfma_f32_16x16x32_bf16 v[44:47], v[170:173], v[230:233], v[44:47]
	v_mfma_f32_16x16x32_bf16 v[36:39], v[162:165], v[238:241], v[36:39]
	v_mfma_f32_16x16x32_bf16 v[28:31], v[170:173], v[238:241], v[28:31]
	v_mfma_f32_16x16x32_bf16 v[20:23], v[162:165], v[246:249], v[20:23]
	v_mfma_f32_16x16x32_bf16 v[12:15], v[170:173], v[246:249], v[12:15]
	v_mfma_f32_16x16x32_bf16 v[48:51], v[194:197], v[178:181], 0
	v_mfma_f32_16x16x32_bf16 v[40:43], v[206:209], v[178:181], 0
	v_mfma_f32_16x16x32_bf16 v[32:35], v[194:197], v[226:229], 0
	v_mfma_f32_16x16x32_bf16 v[24:27], v[206:209], v[226:229], 0
	v_mfma_f32_16x16x32_bf16 v[16:19], v[194:197], v[234:237], 0
	v_mfma_f32_16x16x32_bf16 v[8:11], v[206:209], v[234:237], 0
	v_mfma_f32_16x16x32_bf16 v[4:7], v[194:197], v[242:245], 0
	v_mfma_f32_16x16x32_bf16 v[0:3], v[206:209], v[242:245], 0
	v_mfma_f32_16x16x32_bf16 v[48:51], v[202:205], v[214:217], v[48:51]
	v_mfma_f32_16x16x32_bf16 v[40:43], v[210:213], v[214:217], v[40:43]
	v_mfma_f32_16x16x32_bf16 v[32:35], v[202:205], v[230:233], v[32:35]
	v_mfma_f32_16x16x32_bf16 v[24:27], v[210:213], v[230:233], v[24:27]
	v_mfma_f32_16x16x32_bf16 v[16:19], v[202:205], v[238:241], v[16:19]
	v_mfma_f32_16x16x32_bf16 v[8:11], v[210:213], v[238:241], v[8:11]
	v_mfma_f32_16x16x32_bf16 v[4:7], v[202:205], v[246:249], v[4:7]
	v_mfma_f32_16x16x32_bf16 v[0:3], v[210:213], v[246:249], v[0:3]
	s_barrier
	s_add_i32 s56, 0, 0x18000
	v_add_u32_e32 v142, s56, v145
	s_add_i32 s57, 0, 0x1c000
	ds_read_b128 v[158:161], v142
	ds_read_b128 v[162:165], v142 offset:1024
	ds_read_b128 v[166:169], v142 offset:2048
	ds_read_b128 v[170:173], v142 offset:3072
	v_add_u32_e32 v142, s57, v145
	ds_read_b128 v[178:181], v142
	ds_read_b128 v[194:197], v142 offset:1024
	ds_read_b128 v[202:205], v142 offset:2048
	ds_read_b128 v[206:209], v142 offset:3072
	s_add_u32 s28, s42, 0x40000
	s_addc_u32 s29, s43, 0
	s_mov_b32 m0, s44
	v_lshl_add_u64 v[198:199], s[28:29], 0, v[134:135]
	ds_read_b128 v[210:213], v157 offset:32768
	ds_read_b128 v[214:217], v157 offset:33792
	ds_read_b128 v[226:229], v157 offset:34816
	ds_read_b128 v[230:233], v157 offset:35840
	ds_read_b128 v[234:237], v157 offset:36864
	ds_read_b128 v[238:241], v157 offset:37888
	ds_read_b128 v[242:245], v157 offset:38912
	ds_read_b128 v[246:249], v157 offset:39936
	global_load_lds_dwordx4 v[198:199], off
	v_lshl_add_u64 v[198:199], s[28:29], 0, v[130:131]
	s_mov_b32 m0, s45
	s_nop 0
	global_load_lds_dwordx4 v[198:199], off
	s_waitcnt vmcnt(8)
	s_waitcnt lgkmcnt(0)
	s_barrier
	v_mfma_f32_16x16x32_bf16 v[124:127], v[158:161], v[210:213], v[124:127]
	v_mfma_f32_16x16x32_bf16 v[120:123], v[166:169], v[210:213], v[120:123]
	v_mfma_f32_16x16x32_bf16 v[116:119], v[158:161], v[226:229], v[116:119]
	v_mfma_f32_16x16x32_bf16 v[108:111], v[166:169], v[226:229], v[108:111]
	v_mfma_f32_16x16x32_bf16 v[100:103], v[158:161], v[234:237], v[100:103]
	v_mfma_f32_16x16x32_bf16 v[92:95], v[166:169], v[234:237], v[92:95]
	v_mfma_f32_16x16x32_bf16 v[84:87], v[158:161], v[242:245], v[84:87]
	v_mfma_f32_16x16x32_bf16 v[76:79], v[166:169], v[242:245], v[76:79]
	v_mfma_f32_16x16x32_bf16 v[124:127], v[162:165], v[214:217], v[124:127]
	v_mfma_f32_16x16x32_bf16 v[120:123], v[170:173], v[214:217], v[120:123]
	v_mfma_f32_16x16x32_bf16 v[116:119], v[162:165], v[230:233], v[116:119]
	v_mfma_f32_16x16x32_bf16 v[108:111], v[170:173], v[230:233], v[108:111]
	v_mfma_f32_16x16x32_bf16 v[100:103], v[162:165], v[238:241], v[100:103]
	v_mfma_f32_16x16x32_bf16 v[92:95], v[170:173], v[238:241], v[92:95]
	v_mfma_f32_16x16x32_bf16 v[84:87], v[162:165], v[246:249], v[84:87]
	v_mfma_f32_16x16x32_bf16 v[76:79], v[170:173], v[246:249], v[76:79]
	v_mfma_f32_16x16x32_bf16 v[112:115], v[178:181], v[210:213], v[112:115]
	v_mfma_f32_16x16x32_bf16 v[104:107], v[202:205], v[210:213], v[104:107]
	v_mfma_f32_16x16x32_bf16 v[96:99], v[178:181], v[226:229], v[96:99]
	v_mfma_f32_16x16x32_bf16 v[88:91], v[202:205], v[226:229], v[88:91]
	v_mfma_f32_16x16x32_bf16 v[80:83], v[178:181], v[234:237], v[80:83]
	v_mfma_f32_16x16x32_bf16 v[72:75], v[202:205], v[234:237], v[72:75]
	v_mfma_f32_16x16x32_bf16 v[68:71], v[178:181], v[242:245], v[68:71]
	v_mfma_f32_16x16x32_bf16 v[64:67], v[202:205], v[242:245], v[64:67]
	v_mfma_f32_16x16x32_bf16 v[112:115], v[194:197], v[214:217], v[112:115]
	v_mfma_f32_16x16x32_bf16 v[104:107], v[206:209], v[214:217], v[104:107]
	v_mfma_f32_16x16x32_bf16 v[96:99], v[194:197], v[230:233], v[96:99]
	v_mfma_f32_16x16x32_bf16 v[88:91], v[206:209], v[230:233], v[88:91]
	v_mfma_f32_16x16x32_bf16 v[80:83], v[194:197], v[238:241], v[80:83]
	v_mfma_f32_16x16x32_bf16 v[72:75], v[206:209], v[238:241], v[72:75]
	v_mfma_f32_16x16x32_bf16 v[68:71], v[194:197], v[246:249], v[68:71]
	v_mfma_f32_16x16x32_bf16 v[64:67], v[206:209], v[246:249], v[64:67]
	s_barrier
; #define PG8_STAGE(bufoff, gbase, voff) do { _Pragma("unroll") for (int _i = 0; _i < 2; ++_i) \
;         __builtin_amdgcn_global_load_lds((const unsigned*)((const char*)(gbase) + (voff)[_i]), (LAS unsigned*)(lds + (bufoff) + ldsw + _i * 8192), 16, 0, 0); } while (0)
; #define PG8_LDA(dst, b, h) do { _Pragma("unroll") for (int m = 0; m < 4; ++m) _Pragma("unroll") for (int k = 0; k < 2; ++k) dst[m][k] = *(const LAS bf16x8*)(lds + PG8_SA(b, h) + aoff + m * 2048 + k * 1024); } while (0)
; #define PG8_MMA(ai, bj, At, Bt) do { __builtin_amdgcn_s_setprio(1); _Pragma("unroll") for (int m = 0; m < 4; ++m) _Pragma("unroll") for (int n = 0; n < 2; ++n) _Pragma("unroll") for (int k = 0; k < 2; ++k) \
;         acc[ai][bj][m][n] = __builtin_amdgcn_mfma_f32_16x16x32_bf16(Bt[n][k], At[m][k], acc[ai][bj][m][n], 0, 0, 0); __builtin_amdgcn_s_setprio(0); } while (0)
; #define PG8_WAIT_V(n) asm volatile("s_waitcnt vmcnt(" #n ")" ::: "memory")
; #define PG8_WAIT_L(n) asm volatile("s_waitcnt lgkmcnt(" #n ")" ::: "memory")
; #define PG8_BAR __builtin_amdgcn_s_barrier()
; #define PG8_SCHED __builtin_amdgcn_sched_barrier(0)
; template <class Epi>
; __device__ __forceinline__ void gemm_phase(LAS unsigned char* lds, const Gemm g, const StaticOrder& S, const Epi& E, const int tid) {
;     ...
;             PG8_LDA(At, 1, 1); PG8_STAGE(PG8_SB(1, 0), b3, voffB); PG8_STAGE(PG8_SB(1, 1), b3 + hstepB, voffB); PG8_STAGE(PG8_SA(1, 0), a3, voffA);
;             PG8_WAIT_V(8); PG8_WAIT_L(0); PG8_BAR; PG8_MMA(1, 0, At, B0); PG8_MMA(1, 1, At, B1); PG8_BAR; PG8_SCHED;
;         }
	s_add_i32 s28, s56, s22
	v_lshl_add_u64 v[146:147], v[146:147], 0, s[36:37]
	s_mov_b32 m0, s28
	ds_read_b128 v[210:213], v157 offset:49152
	ds_read_b128 v[214:217], v157 offset:50176
	ds_read_b128 v[226:229], v157 offset:51200
	ds_read_b128 v[230:233], v157 offset:52224
	ds_read_b128 v[234:237], v157 offset:53248
	ds_read_b128 v[238:241], v157 offset:54272
	ds_read_b128 v[242:245], v157 offset:55296
	ds_read_b128 v[246:249], v157 offset:56320
	global_load_lds_dwordx4 v[146:147], off
	s_add_i32 m0, s28, 0x2000
	s_add_u32 s28, s40, 0x40080
	v_lshl_add_u64 v[146:147], v[150:151], 0, s[36:37]
	s_addc_u32 s29, s41, 0
	s_add_i32 s40, s57, s22
	global_load_lds_dwordx4 v[146:147], off
	v_lshl_add_u64 v[146:147], s[28:29], 0, v[132:133]
	s_mov_b32 m0, s40
	s_nop 0
	global_load_lds_dwordx4 v[146:147], off
	v_lshl_add_u64 v[146:147], s[28:29], 0, v[128:129]
	s_add_i32 m0, s40, 0x2000
	s_nop 0
	global_load_lds_dwordx4 v[146:147], off
	v_lshl_add_u64 v[146:147], v[154:155], 0, s[76:77]
	s_mov_b32 m0, s46
	s_nop 0
	global_load_lds_dwordx4 v[146:147], off
	v_lshl_add_u64 v[146:147], v[174:175], 0, s[76:77]
	s_mov_b32 m0, s47
	s_nop 0
	global_load_lds_dwordx4 v[146:147], off
	s_waitcnt vmcnt(8)
	s_waitcnt lgkmcnt(0)
	s_barrier
	v_mfma_f32_16x16x32_bf16 v[60:63], v[158:161], v[210:213], v[60:63]
	v_mfma_f32_16x16x32_bf16 v[56:59], v[166:169], v[210:213], v[56:59]
	v_mfma_f32_16x16x32_bf16 v[52:55], v[158:161], v[226:229], v[52:55]
	v_mfma_f32_16x16x32_bf16 v[44:47], v[166:169], v[226:229], v[44:47]
	v_mfma_f32_16x16x32_bf16 v[36:39], v[158:161], v[234:237], v[36:39]
	v_mfma_f32_16x16x32_bf16 v[28:31], v[166:169], v[234:237], v[28:31]
	v_mfma_f32_16x16x32_bf16 v[20:23], v[158:161], v[242:245], v[20:23]
	v_mfma_f32_16x16x32_bf16 v[12:15], v[166:169], v[242:245], v[12:15]
	v_mfma_f32_16x16x32_bf16 v[60:63], v[162:165], v[214:217], v[60:63]
	v_mfma_f32_16x16x32_bf16 v[56:59], v[170:173], v[214:217], v[56:59]
	v_mfma_f32_16x16x32_bf16 v[52:55], v[162:165], v[230:233], v[52:55]
	v_mfma_f32_16x16x32_bf16 v[44:47], v[170:173], v[230:233], v[44:47]
	v_mfma_f32_16x16x32_bf16 v[36:39], v[162:165], v[238:241], v[36:39]
	v_mfma_f32_16x16x32_bf16 v[28:31], v[170:173], v[238:241], v[28:31]
	v_mfma_f32_16x16x32_bf16 v[20:23], v[162:165], v[246:249], v[20:23]
	v_mfma_f32_16x16x32_bf16 v[12:15], v[170:173], v[246:249], v[12:15]
	v_mfma_f32_16x16x32_bf16 v[48:51], v[178:181], v[210:213], v[48:51]
	v_mfma_f32_16x16x32_bf16 v[40:43], v[202:205], v[210:213], v[40:43]
	v_mfma_f32_16x16x32_bf16 v[32:35], v[178:181], v[226:229], v[32:35]
	v_mfma_f32_16x16x32_bf16 v[24:27], v[202:205], v[226:229], v[24:27]
	v_mfma_f32_16x16x32_bf16 v[16:19], v[178:181], v[234:237], v[16:19]
	v_mfma_f32_16x16x32_bf16 v[8:11], v[202:205], v[234:237], v[8:11]
	v_mfma_f32_16x16x32_bf16 v[4:7], v[178:181], v[242:245], v[4:7]
	v_mfma_f32_16x16x32_bf16 v[0:3], v[202:205], v[242:245], v[0:3]
	v_mfma_f32_16x16x32_bf16 v[48:51], v[194:197], v[214:217], v[48:51]
	v_mfma_f32_16x16x32_bf16 v[40:43], v[206:209], v[214:217], v[40:43]
	v_mfma_f32_16x16x32_bf16 v[32:35], v[194:197], v[230:233], v[32:35]
	v_mfma_f32_16x16x32_bf16 v[24:27], v[206:209], v[230:233], v[24:27]
	v_mfma_f32_16x16x32_bf16 v[16:19], v[194:197], v[238:241], v[16:19]
	v_mfma_f32_16x16x32_bf16 v[8:11], v[206:209], v[238:241], v[8:11]
	v_mfma_f32_16x16x32_bf16 v[4:7], v[194:197], v[246:249], v[4:7]
	v_mfma_f32_16x16x32_bf16 v[0:3], v[206:209], v[246:249], v[0:3]
	s_barrier
	s_add_i32 s55, s55, 2
	s_add_u32 s53, s53, 0x100
	s_addc_u32 s54, s54, 0
	s_mov_b64 s[28:29], s[34:35]
